# weight-copy loops: wait moved so next item's loads overlap transpose/stores (5 instances); plus earlier de-serialised loads
# baseline (speedup 1.0000x reference)
; __device__ __forceinline__ void tr_load(const TrItem& t, f32x4 (&v)[16], int lane) {
;     const int c4 = 4 * (lane & 15), kq = lane >> 4; const bool okc = t.n0 + c4 < t.N;
; #pragma unroll
;     for (int i = 0; i < 16; ++i) { v[i] = (f32x4){0.f, 0.f, 0.f, 0.f}; if (okc) v[i] = *(const f32x4*)(t.W + (size_t)(t.k0 + 4 * i + kq) * t.N + t.n0 + c4); }
;     ...
;     TrItem tc, tn; f32x4 vc[16], vn[16];
;     int it = it0 + gw;
;     if (it < it1) { TR_DESCRIBE(it, tc); tr_load(tc, vc, lane); }
;     for (; it < it1; it += NGW) {
;         const bool more = it + NGW < it1;
;         if (more) { TR_DESCRIBE(it + NGW, tn); tr_load(tn, vn, lane); }
.LBB0_311:
	s_waitcnt vmcnt(0)
	s_add_i32 s18, s18, s27
	s_cmpk_lt_i32 s18, 0xb00
	s_cselect_b64 s[14:15], -1, 0
	s_cmpk_gt_i32 s18, 0xaff
	s_cselect_b64 s[12:13], -1, 0
	s_and_b64 vcc, exec, s[12:13]
	s_cbranch_vccnz .LBB0_329
	s_mul_hi_i32 s9, s18, 0x2e8ba2e9
	s_lshr_b32 s10, s9, 31
	s_ashr_i32 s22, s9, 5
	s_add_i32 s22, s22, s10
	s_mul_i32 s9, s22, 0xffffd400
	s_add_i32 s10, s7, s9
	v_mov_b32_e32 v72, v3
	v_mov_b32_e32 v73, v3
	v_add_u32_e32 v2, s10, v138
	v_mov_b32_e32 v70, v3
	v_mov_b32_e32 v71, v3
	v_mov_b64_e32 v[76:77], v[72:73]
	v_mov_b64_e32 v[80:81], v[72:73]
	s_lshl_b32 s21, s22, 6
	v_cmp_gt_i32_e32 vcc, s30, v2
	v_lshlrev_b32_e32 v134, 2, v138
	v_mov_b64_e32 v[74:75], v[70:71]
	v_mov_b64_e32 v[78:79], v[70:71]
	s_and_saveexec_b64 s[16:17], vcc
	s_cbranch_execz .LBB0_314
	v_or_b32_e32 v2, s21, v139
	v_mov_b64_e32 v[4:5], s[0:1]
	v_mad_i64_i32 v[74:75], s[24:25], v2, s31, v[4:5]
	s_ashr_i32 s11, s10, 31
	s_lshl_b64 s[24:25], s[10:11], 2
	v_or_b32_e32 v2, 4, v2
	v_lshl_add_u64 v[74:75], v[74:75], 0, s[24:25]
	v_mov_b32_e32 v135, v3
	v_mad_i64_i32 v[4:5], s[28:29], v2, s31, v[4:5]
	v_lshl_add_u64 v[74:75], v[74:75], 0, v[134:135]
	v_lshl_add_u64 v[4:5], v[4:5], 0, s[24:25]
	v_lshl_add_u64 v[4:5], v[4:5], 0, v[134:135]
	global_load_dwordx4 v[78:81], v[74:75], off
	s_nop 0
	global_load_dwordx4 v[74:77], v[4:5], off

; #define LAS __attribute__((address_space(3)))
; __device__ __forceinline__ unsigned pk2(float lo, float hi) { return cvtpk(lo, hi); }
; __device__ __forceinline__ void tr_finish(const TrItem& t, const f32x4 (&v)[16], LAS float* scr, int lane) {
;     const int c4 = 4 * (lane & 15), kq = lane >> 4;
; #pragma unroll
;     for (int i = 0; i < 16; ++i) { LAS float* d = scr + (4 * i + kq) * 65 + c4; d[0] = v[i].x; d[1] = v[i].y; d[2] = v[i].z; d[3] = v[i].w; }
;     asm volatile("s_waitcnt lgkmcnt(0)" ::: "memory");
;     const int c = lane & 7;
; #pragma unroll
;     for (int j = 0; j < 8; ++j) { const int n = (lane >> 3) + 8 * j; const LAS float* s = scr + (8 * c) * 65 + n;
;         v4u o; o.x = pk2(s[0 * 65], s[1 * 65]); o.y = pk2(s[2 * 65], s[3 * 65]); o.z = pk2(s[4 * 65], s[5 * 65]); o.w = pk2(s[6 * 65], s[7 * 65]);
;         if (t.n0 + n < t.N) *(v4u*)(t.WT + (size_t)(t.drow0 + n) * t.K + t.k0 + 8 * c) = o; }
;     asm volatile("s_waitcnt lgkmcnt(0)" ::: "memory");
.LBB0_329:
	v_add_u32_e32 v2, 0x410, v158
	ds_write2_b32 v158, v6, v7 offset1:1
	ds_write2_b32 v158, v8, v9 offset0:2 offset1:3
	ds_write2_b32 v2, v10, v11 offset1:1
	v_add_u32_e32 v2, 0x418, v158
	ds_write2_b32 v2, v12, v13 offset1:1
	v_add_u32_e32 v2, 0x820, v158
	ds_write2_b32 v2, v14, v15 offset1:1
	v_add_u32_e32 v2, 0x828, v158
	ds_write2_b32 v2, v16, v17 offset1:1
	v_add_u32_e32 v2, 0xc30, v158
	ds_write2_b32 v2, v18, v19 offset1:1
	v_add_u32_e32 v2, 0xc38, v158
	ds_write2_b32 v2, v20, v21 offset1:1
	v_add_u32_e32 v2, 0x1040, v158
	ds_write2_b32 v2, v22, v23 offset1:1
	v_add_u32_e32 v2, 0x1048, v158
	ds_write2_b32 v2, v24, v25 offset1:1
	v_add_u32_e32 v2, 0x1450, v158
	ds_write2_b32 v2, v26, v27 offset1:1
	v_add_u32_e32 v2, 0x1458, v158
	ds_write2_b32 v2, v28, v29 offset1:1
	v_add_u32_e32 v2, 0x1860, v158
	ds_write2_b32 v2, v30, v31 offset1:1
	v_add_u32_e32 v2, 0x1868, v158
	ds_write2_b32 v2, v32, v33 offset1:1
	v_add_u32_e32 v2, 0x1c70, v158
	ds_write2_b32 v2, v34, v35 offset1:1
	v_add_u32_e32 v2, 0x1c78, v158
	ds_write2_b32 v2, v36, v37 offset1:1
	v_add_u32_e32 v2, 0x2080, v158
	ds_write2_b32 v2, v38, v39 offset1:1
	v_add_u32_e32 v2, 0x2088, v158
	ds_write2_b32 v2, v40, v41 offset1:1
	v_add_u32_e32 v2, 0x2490, v158
	ds_write2_b32 v2, v42, v43 offset1:1
	v_add_u32_e32 v2, 0x2498, v158
	ds_write2_b32 v2, v44, v45 offset1:1
	v_add_u32_e32 v2, 0x28a0, v158
	ds_write2_b32 v2, v46, v47 offset1:1
	v_add_u32_e32 v2, 0x28a8, v158
	ds_write2_b32 v2, v48, v49 offset1:1
	v_add_u32_e32 v2, 0x2cb0, v158
	ds_write2_b32 v2, v50, v51 offset1:1
	v_add_u32_e32 v2, 0x2cb8, v158
	ds_write2_b32 v2, v52, v53 offset1:1
	v_add_u32_e32 v2, 0x30c0, v158
	ds_write2_b32 v2, v54, v55 offset1:1
	v_add_u32_e32 v2, 0x30c8, v158
	ds_write2_b32 v2, v56, v57 offset1:1
	v_add_u32_e32 v2, 0x34d0, v158
	ds_write2_b32 v2, v58, v59 offset1:1
	v_add_u32_e32 v2, 0x34d8, v158
	ds_write2_b32 v2, v60, v61 offset1:1
	v_add_u32_e32 v2, 0x38e0, v158
	ds_write2_b32 v2, v62, v63 offset1:1
	v_add_u32_e32 v2, 0x38e8, v158
	ds_write2_b32 v2, v64, v65 offset1:1
	v_add_u32_e32 v2, 0x3cf0, v158
	ds_write2_b32 v2, v66, v67 offset1:1
	v_add_u32_e32 v2, 0x3cf8, v158
	ds_write2_b32 v2, v68, v69 offset1:1
	s_waitcnt lgkmcnt(0)
	ds_read2_b32 v[4:5], v142 offset1:65
	s_waitcnt lgkmcnt(0)
	v_cvt_pk_bf16_f32 v134, v4, v5
	ds_read2_b32 v[4:5], v142 offset0:130 offset1:195
	s_waitcnt lgkmcnt(0)
	v_cvt_pk_bf16_f32 v135, v4, v5
	v_add_u32_e32 v4, 0x400, v142
	ds_read2_b32 v[136:137], v4 offset0:4 offset1:69
	v_cmp_lt_i32_e32 vcc, s6, v150
	v_lshlrev_b32_e32 v2, 1, v140
	s_waitcnt lgkmcnt(0)
	v_cvt_pk_bf16_f32 v136, v136, v137
	ds_read2_b32 v[160:161], v4 offset0:134 offset1:199
	s_waitcnt lgkmcnt(0)
	v_cvt_pk_bf16_f32 v137, v160, v161
	s_and_saveexec_b64 s[16:17], vcc
	s_cbranch_execz .LBB0_331
	v_add_u32_e32 v160, s19, v141
	v_ashrrev_i32_e32 v161, 31, v160
	v_lshlrev_b64 v[160:161], 12, v[160:161]
	v_lshl_add_u64 v[160:161], s[4:5], 0, v[160:161]
	s_ashr_i32 s9, s8, 31
	v_lshl_add_u64 v[160:161], s[8:9], 1, v[160:161]
	v_lshl_add_u64 v[160:161], v[160:161], 0, v[2:3]
	global_store_dwordx4 v[160:161], v[134:137], off

;     ...
;     for (; it < it1; it += NGW) {
;         const bool more = it + NGW < it1;
;         if (more) { TR_DESCRIBE(it + NGW, tn); tr_load(tn, vn, lane); }
;         tr_finish(tc, vc, scr, lane);
;         if (more) { tc = tn;
; #pragma unroll
;             for (int i = 0; i < 16; ++i) vc[i] = vn[i]; }
.LBB0_345:
	s_or_b64 exec, exec, s[16:17]
	s_waitcnt lgkmcnt(0)
	s_andn2_b64 vcc, exec, s[14:15]
	s_cbranch_vccnz .LBB0_310
	s_waitcnt vmcnt(0)
	v_mov_b64_e32 v[66:67], v[130:131]
	v_mov_b64_e32 v[62:63], v[126:127]
	v_mov_b64_e32 v[58:59], v[118:119]
	v_mov_b64_e32 v[54:55], v[122:123]
	v_mov_b64_e32 v[50:51], v[110:111]
	v_mov_b64_e32 v[46:47], v[114:115]
	v_mov_b64_e32 v[42:43], v[102:103]
	v_mov_b64_e32 v[38:39], v[106:107]
	v_mov_b64_e32 v[34:35], v[94:95]
	v_mov_b64_e32 v[30:31], v[98:99]
	v_mov_b64_e32 v[26:27], v[86:87]
	v_mov_b64_e32 v[22:23], v[90:91]
	v_mov_b64_e32 v[18:19], v[70:71]
	v_mov_b64_e32 v[14:15], v[82:83]
	v_mov_b64_e32 v[10:11], v[74:75]
	v_mov_b64_e32 v[6:7], v[78:79]
	v_mov_b64_e32 v[68:69], v[132:133]
	v_mov_b64_e32 v[64:65], v[128:129]
	v_mov_b64_e32 v[60:61], v[120:121]
	v_mov_b64_e32 v[56:57], v[124:125]
	v_mov_b64_e32 v[52:53], v[112:113]
	v_mov_b64_e32 v[48:49], v[116:117]
	v_mov_b64_e32 v[44:45], v[104:105]
	v_mov_b64_e32 v[40:41], v[108:109]
	v_mov_b64_e32 v[36:37], v[96:97]
	v_mov_b64_e32 v[32:33], v[100:101]
	v_mov_b64_e32 v[28:29], v[88:89]
	v_mov_b64_e32 v[24:25], v[92:93]
	v_mov_b64_e32 v[20:21], v[72:73]
	v_mov_b64_e32 v[16:17], v[84:85]
	v_mov_b64_e32 v[12:13], v[76:77]
	v_mov_b64_e32 v[8:9], v[80:81]
	s_mov_b32 s8, s21
	s_mov_b32 s19, s11
	s_mov_b32 s6, s10
	s_branch .LBB0_310

;     ...
;     TrItem tc, tn; f32x4 vc[16], vn[16];
;     int it = it0 + gw;
;     if (it < it1) { TR_DESCRIBE(it, tc); tr_load(tc, vc, lane); }
;     for (; it < it1; it += NGW) {
;         const bool more = it + NGW < it1;
;         if (more) { TR_DESCRIBE(it + NGW, tn); tr_load(tn, vn, lane); }
.LBB0_468:
	s_waitcnt vmcnt(0)
	v_readlane_b32 s15, v252, 51
	s_add_i32 s33, s15, s33
	s_cmpk_lt_i32 s33, 0x2500
	s_cselect_b64 s[26:27], -1, 0
	s_cmpk_gt_i32 s33, 0x24ff
	s_cselect_b64 s[24:25], -1, 0
	s_and_b64 vcc, exec, s[24:25]
	s_cbranch_vccnz .LBB0_494
	s_cmpk_gt_i32 s33, 0x15ff
	s_mov_b64 s[30:31], -1
	s_cbranch_scc0 .LBB0_475
	s_cmpk_gt_u32 s33, 0x20ff
	s_mov_b64 s[20:21], -1
	s_cbranch_scc0 .LBB0_472
	s_add_i32 s15, s39, 0x1be00
	s_and_b32 s41, s15, 0x1ffc0
	s_mov_b64 s[20:21], 0

; #define LAS __attribute__((address_space(3)))
; __device__ __forceinline__ unsigned pk2(float lo, float hi) { return cvtpk(lo, hi); }
; __device__ __forceinline__ void tr_finish(const TrItem& t, const f32x4 (&v)[16], LAS float* scr, int lane) {
;     const int c4 = 4 * (lane & 15), kq = lane >> 4;
; #pragma unroll
;     for (int i = 0; i < 16; ++i) { LAS float* d = scr + (4 * i + kq) * 65 + c4; d[0] = v[i].x; d[1] = v[i].y; d[2] = v[i].z; d[3] = v[i].w; }
;     asm volatile("s_waitcnt lgkmcnt(0)" ::: "memory");
;     const int c = lane & 7;
; #pragma unroll
;     for (int j = 0; j < 8; ++j) { const int n = (lane >> 3) + 8 * j; const LAS float* s = scr + (8 * c) * 65 + n;
;         v4u o; o.x = pk2(s[0 * 65], s[1 * 65]); o.y = pk2(s[2 * 65], s[3 * 65]); o.z = pk2(s[4 * 65], s[5 * 65]); o.w = pk2(s[6 * 65], s[7 * 65]);
;         if (t.n0 + n < t.N) *(v4u*)(t.WT + (size_t)(t.drow0 + n) * t.K + t.k0 + 8 * c) = o; }
;     asm volatile("s_waitcnt lgkmcnt(0)" ::: "memory");
.LBB0_494:
	v_add_u32_e32 v2, 0x410, v165
	ds_write2_b32 v165, v6, v7 offset1:1
	ds_write2_b32 v165, v8, v9 offset0:2 offset1:3
	ds_write2_b32 v2, v10, v11 offset1:1
	v_add_u32_e32 v2, 0x418, v165
	ds_write2_b32 v2, v12, v13 offset1:1
	v_add_u32_e32 v2, 0x820, v165
	ds_write2_b32 v2, v14, v15 offset1:1
	v_add_u32_e32 v2, 0x828, v165
	ds_write2_b32 v2, v16, v17 offset1:1
	v_add_u32_e32 v2, 0xc30, v165
	ds_write2_b32 v2, v18, v19 offset1:1
	v_add_u32_e32 v2, 0xc38, v165
	ds_write2_b32 v2, v20, v21 offset1:1
	v_add_u32_e32 v2, 0x1040, v165
	ds_write2_b32 v2, v22, v23 offset1:1
	v_add_u32_e32 v2, 0x1048, v165
	ds_write2_b32 v2, v24, v25 offset1:1
	v_add_u32_e32 v2, 0x1450, v165
	ds_write2_b32 v2, v26, v27 offset1:1
	v_add_u32_e32 v2, 0x1458, v165
	ds_write2_b32 v2, v28, v29 offset1:1
	v_add_u32_e32 v2, 0x1860, v165
	ds_write2_b32 v2, v30, v31 offset1:1
	v_add_u32_e32 v2, 0x1868, v165
	ds_write2_b32 v2, v32, v33 offset1:1
	v_add_u32_e32 v2, 0x1c70, v165
	ds_write2_b32 v2, v34, v35 offset1:1
	v_add_u32_e32 v2, 0x1c78, v165
	ds_write2_b32 v2, v36, v37 offset1:1
	v_add_u32_e32 v2, 0x2080, v165
	ds_write2_b32 v2, v38, v39 offset1:1
	v_add_u32_e32 v2, 0x2088, v165
	ds_write2_b32 v2, v40, v41 offset1:1
	v_add_u32_e32 v2, 0x2490, v165
	ds_write2_b32 v2, v42, v43 offset1:1
	v_add_u32_e32 v2, 0x2498, v165
	ds_write2_b32 v2, v44, v45 offset1:1
	v_add_u32_e32 v2, 0x28a0, v165
	ds_write2_b32 v2, v46, v47 offset1:1
	v_add_u32_e32 v2, 0x28a8, v165
	ds_write2_b32 v2, v48, v49 offset1:1
	v_add_u32_e32 v2, 0x2cb0, v165
	ds_write2_b32 v2, v50, v51 offset1:1
	v_add_u32_e32 v2, 0x2cb8, v165
	ds_write2_b32 v2, v52, v53 offset1:1
	v_add_u32_e32 v2, 0x30c0, v165
	ds_write2_b32 v2, v54, v55 offset1:1
	v_add_u32_e32 v2, 0x30c8, v165
	ds_write2_b32 v2, v56, v57 offset1:1
	v_add_u32_e32 v2, 0x34d0, v165
	ds_write2_b32 v2, v58, v59 offset1:1
	v_add_u32_e32 v2, 0x34d8, v165
	ds_write2_b32 v2, v60, v61 offset1:1
	v_add_u32_e32 v2, 0x38e0, v165
	ds_write2_b32 v2, v62, v63 offset1:1
	v_add_u32_e32 v2, 0x38e8, v165
	ds_write2_b32 v2, v64, v65 offset1:1
	v_add_u32_e32 v2, 0x3cf0, v165
	ds_write2_b32 v2, v66, v67 offset1:1
	v_add_u32_e32 v2, 0x3cf8, v165
	ds_write2_b32 v2, v68, v69 offset1:1
	s_waitcnt lgkmcnt(0)
	ds_read2_b32 v[4:5], v157 offset1:65
	s_waitcnt lgkmcnt(0)
	v_cvt_pk_bf16_f32 v134, v4, v5
	ds_read2_b32 v[4:5], v157 offset0:130 offset1:195
	s_waitcnt lgkmcnt(0)
	v_cvt_pk_bf16_f32 v135, v4, v5
	v_add_u32_e32 v4, 0x400, v157
	v_add_u32_e32 v2, s18, v156
	ds_read2_b32 v[136:137], v4 offset0:4 offset1:69
	v_cmp_gt_i32_e32 vcc, s37, v2
	v_lshlrev_b32_e32 v2, 1, v140
	s_waitcnt lgkmcnt(0)
	v_cvt_pk_bf16_f32 v136, v136, v137
	ds_read2_b32 v[166:167], v4 offset0:134 offset1:199
	s_waitcnt lgkmcnt(0)
	v_cvt_pk_bf16_f32 v137, v166, v167
	s_and_saveexec_b64 s[28:29], vcc
	s_cbranch_execz .LBB0_496
	v_add_u32_e32 v5, s36, v156
	v_mad_i64_i32 v[166:167], s[30:31], v5, s35, 0
	v_lshl_add_u64 v[166:167], v[166:167], 1, s[16:17]
	s_ashr_i32 s15, s14, 31
	v_lshl_add_u64 v[166:167], s[14:15], 1, v[166:167]
	v_lshl_add_u64 v[166:167], v[166:167], 0, v[2:3]
	global_store_dwordx4 v[166:167], v[134:137], off

;     ...
;     for (; it < it1; it += NGW) {
;         const bool more = it + NGW < it1;
;         if (more) { TR_DESCRIBE(it + NGW, tn); tr_load(tn, vn, lane); }
;         tr_finish(tc, vc, scr, lane);
;         if (more) { tc = tn;
; #pragma unroll
;             for (int i = 0; i < 16; ++i) vc[i] = vn[i]; }
.LBB0_510:
	s_or_b64 exec, exec, s[28:29]
	s_waitcnt lgkmcnt(0)
	s_andn2_b64 vcc, exec, s[26:27]
	s_cbranch_vccnz .LBB0_467
	s_waitcnt vmcnt(0)
	v_mov_b64_e32 v[66:67], v[130:131]
	v_mov_b64_e32 v[62:63], v[126:127]
	v_mov_b64_e32 v[58:59], v[118:119]
	v_mov_b64_e32 v[54:55], v[122:123]
	v_mov_b64_e32 v[50:51], v[110:111]
	v_mov_b64_e32 v[46:47], v[114:115]
	v_mov_b64_e32 v[42:43], v[102:103]
	v_mov_b64_e32 v[38:39], v[106:107]
	v_mov_b64_e32 v[34:35], v[94:95]
	v_mov_b64_e32 v[30:31], v[98:99]
	v_mov_b64_e32 v[26:27], v[86:87]
	v_mov_b64_e32 v[22:23], v[90:91]
	v_mov_b64_e32 v[18:19], v[78:79]
	v_mov_b64_e32 v[14:15], v[82:83]
	v_mov_b64_e32 v[10:11], v[70:71]
	v_mov_b64_e32 v[6:7], v[74:75]
	v_mov_b64_e32 v[68:69], v[132:133]
	v_mov_b64_e32 v[64:65], v[128:129]
	v_mov_b64_e32 v[60:61], v[120:121]
	v_mov_b64_e32 v[56:57], v[124:125]
	v_mov_b64_e32 v[52:53], v[112:113]
	v_mov_b64_e32 v[48:49], v[116:117]
	v_mov_b64_e32 v[44:45], v[104:105]
	v_mov_b64_e32 v[40:41], v[108:109]
	v_mov_b64_e32 v[36:37], v[96:97]
	v_mov_b64_e32 v[32:33], v[100:101]
	v_mov_b64_e32 v[28:29], v[88:89]
	v_mov_b64_e32 v[24:25], v[92:93]
	v_mov_b64_e32 v[20:21], v[80:81]
	v_mov_b64_e32 v[16:17], v[84:85]
	v_mov_b64_e32 v[12:13], v[72:73]
	v_mov_b64_e32 v[8:9], v[76:77]
	s_mov_b32 s14, s41
	s_mov_b32 s36, s44
	s_mov_b32 s37, s43
	s_mov_b32 s35, s42
	s_mov_b64 s[16:17], s[20:21]
	s_mov_b32 s18, s22
	s_branch .LBB0_467

; __device__ __forceinline__ void tr_load(const TrItem& t, f32x4 (&v)[16], int lane) {
;     const int c4 = 4 * (lane & 15), kq = lane >> 4; const bool okc = t.n0 + c4 < t.N;
; #pragma unroll
;     for (int i = 0; i < 16; ++i) { v[i] = (f32x4){0.f, 0.f, 0.f, 0.f}; if (okc) v[i] = *(const f32x4*)(t.W + (size_t)(t.k0 + 4 * i + kq) * t.N + t.n0 + c4); }
;     ...
;     TrItem tc, tn; f32x4 vc[16], vn[16];
;     int it = it0 + gw;
;     if (it < it1) { TR_DESCRIBE(it, tc); tr_load(tc, vc, lane); }
;     for (; it < it1; it += NGW) {
;         const bool more = it + NGW < it1;
;         if (more) { TR_DESCRIBE(it + NGW, tn); tr_load(tn, vn, lane); }
.LBB0_678:
	s_waitcnt vmcnt(0)
	v_readlane_b32 s7, v253, 5
	s_add_i32 s16, s16, s7
	s_cmpk_lt_i32 s16, 0x1600
	s_cselect_b64 s[12:13], -1, 0
	s_cmpk_gt_i32 s16, 0x15ff
	s_cselect_b64 s[10:11], -1, 0
	s_and_b64 vcc, exec, s[10:11]
	s_cbranch_vccnz .LBB0_696
	s_mul_hi_i32 s7, s16, 0x2e8ba2e9
	s_lshr_b32 s8, s7, 31
	s_ashr_i32 s20, s7, 5
	s_add_i32 s20, s20, s8
	s_mul_i32 s7, s20, 0xffffd400
	s_add_i32 s8, s5, s7
	v_mov_b32_e32 v72, v3
	v_mov_b32_e32 v73, v3
	v_add_u32_e32 v2, s8, v138
	v_mov_b32_e32 v70, v3
	v_mov_b32_e32 v71, v3
	v_mov_b64_e32 v[76:77], v[72:73]
	v_mov_b64_e32 v[80:81], v[72:73]
	s_lshl_b32 s19, s20, 6
	v_cmp_gt_i32_e32 vcc, s25, v2
	v_lshlrev_b32_e32 v134, 2, v138
	v_mov_b64_e32 v[74:75], v[70:71]
	v_mov_b64_e32 v[78:79], v[70:71]
	s_and_saveexec_b64 s[14:15], vcc
	s_cbranch_execz .LBB0_681
	v_or_b32_e32 v2, s19, v139
	v_mov_b64_e32 v[4:5], s[0:1]
	v_mad_i64_i32 v[74:75], s[22:23], v2, s28, v[4:5]
	s_ashr_i32 s9, s8, 31
	s_lshl_b64 s[22:23], s[8:9], 2
	v_or_b32_e32 v2, 4, v2
	v_lshl_add_u64 v[74:75], v[74:75], 0, s[22:23]
	v_mov_b32_e32 v135, v3
	v_mad_i64_i32 v[4:5], s[26:27], v2, s28, v[4:5]
	v_lshl_add_u64 v[74:75], v[74:75], 0, v[134:135]
	v_lshl_add_u64 v[4:5], v[4:5], 0, s[22:23]
	v_lshl_add_u64 v[4:5], v[4:5], 0, v[134:135]
	global_load_dwordx4 v[78:81], v[74:75], off
	s_nop 0
	global_load_dwordx4 v[74:77], v[4:5], off

; #define LAS __attribute__((address_space(3)))
; __device__ __forceinline__ unsigned pk2(float lo, float hi) { return cvtpk(lo, hi); }
; __device__ __forceinline__ void tr_finish(const TrItem& t, const f32x4 (&v)[16], LAS float* scr, int lane) {
;     const int c4 = 4 * (lane & 15), kq = lane >> 4;
; #pragma unroll
;     for (int i = 0; i < 16; ++i) { LAS float* d = scr + (4 * i + kq) * 65 + c4; d[0] = v[i].x; d[1] = v[i].y; d[2] = v[i].z; d[3] = v[i].w; }
;     asm volatile("s_waitcnt lgkmcnt(0)" ::: "memory");
;     const int c = lane & 7;
; #pragma unroll
;     for (int j = 0; j < 8; ++j) { const int n = (lane >> 3) + 8 * j; const LAS float* s = scr + (8 * c) * 65 + n;
;         v4u o; o.x = pk2(s[0 * 65], s[1 * 65]); o.y = pk2(s[2 * 65], s[3 * 65]); o.z = pk2(s[4 * 65], s[5 * 65]); o.w = pk2(s[6 * 65], s[7 * 65]);
;         if (t.n0 + n < t.N) *(v4u*)(t.WT + (size_t)(t.drow0 + n) * t.K + t.k0 + 8 * c) = o; }
;     asm volatile("s_waitcnt lgkmcnt(0)" ::: "memory");
.LBB0_696:
	v_add_u32_e32 v2, 0x410, v158
	ds_write2_b32 v158, v6, v7 offset1:1
	ds_write2_b32 v158, v8, v9 offset0:2 offset1:3
	ds_write2_b32 v2, v10, v11 offset1:1
	v_add_u32_e32 v2, 0x418, v158
	ds_write2_b32 v2, v12, v13 offset1:1
	v_add_u32_e32 v2, 0x820, v158
	ds_write2_b32 v2, v14, v15 offset1:1
	v_add_u32_e32 v2, 0x828, v158
	ds_write2_b32 v2, v16, v17 offset1:1
	v_add_u32_e32 v2, 0xc30, v158
	ds_write2_b32 v2, v18, v19 offset1:1
	v_add_u32_e32 v2, 0xc38, v158
	ds_write2_b32 v2, v20, v21 offset1:1
	v_add_u32_e32 v2, 0x1040, v158
	ds_write2_b32 v2, v22, v23 offset1:1
	v_add_u32_e32 v2, 0x1048, v158
	ds_write2_b32 v2, v24, v25 offset1:1
	v_add_u32_e32 v2, 0x1450, v158
	ds_write2_b32 v2, v26, v27 offset1:1
	v_add_u32_e32 v2, 0x1458, v158
	ds_write2_b32 v2, v28, v29 offset1:1
	v_add_u32_e32 v2, 0x1860, v158
	ds_write2_b32 v2, v30, v31 offset1:1
	v_add_u32_e32 v2, 0x1868, v158
	ds_write2_b32 v2, v32, v33 offset1:1
	v_add_u32_e32 v2, 0x1c70, v158
	ds_write2_b32 v2, v34, v35 offset1:1
	v_add_u32_e32 v2, 0x1c78, v158
	ds_write2_b32 v2, v36, v37 offset1:1
	v_add_u32_e32 v2, 0x2080, v158
	ds_write2_b32 v2, v38, v39 offset1:1
	v_add_u32_e32 v2, 0x2088, v158
	ds_write2_b32 v2, v40, v41 offset1:1
	v_add_u32_e32 v2, 0x2490, v158
	ds_write2_b32 v2, v42, v43 offset1:1
	v_add_u32_e32 v2, 0x2498, v158
	ds_write2_b32 v2, v44, v45 offset1:1
	v_add_u32_e32 v2, 0x28a0, v158
	ds_write2_b32 v2, v46, v47 offset1:1
	v_add_u32_e32 v2, 0x28a8, v158
	ds_write2_b32 v2, v48, v49 offset1:1
	v_add_u32_e32 v2, 0x2cb0, v158
	ds_write2_b32 v2, v50, v51 offset1:1
	v_add_u32_e32 v2, 0x2cb8, v158
	ds_write2_b32 v2, v52, v53 offset1:1
	v_add_u32_e32 v2, 0x30c0, v158
	ds_write2_b32 v2, v54, v55 offset1:1
	v_add_u32_e32 v2, 0x30c8, v158
	ds_write2_b32 v2, v56, v57 offset1:1
	v_add_u32_e32 v2, 0x34d0, v158
	ds_write2_b32 v2, v58, v59 offset1:1
	v_add_u32_e32 v2, 0x34d8, v158
	ds_write2_b32 v2, v60, v61 offset1:1
	v_add_u32_e32 v2, 0x38e0, v158
	ds_write2_b32 v2, v62, v63 offset1:1
	v_add_u32_e32 v2, 0x38e8, v158
	ds_write2_b32 v2, v64, v65 offset1:1
	v_add_u32_e32 v2, 0x3cf0, v158
	ds_write2_b32 v2, v66, v67 offset1:1
	v_add_u32_e32 v2, 0x3cf8, v158
	ds_write2_b32 v2, v68, v69 offset1:1
	s_waitcnt lgkmcnt(0)
	ds_read2_b32 v[4:5], v142 offset1:65
	s_waitcnt lgkmcnt(0)
	v_cvt_pk_bf16_f32 v134, v4, v5
	ds_read2_b32 v[4:5], v142 offset0:130 offset1:195
	s_waitcnt lgkmcnt(0)
	v_cvt_pk_bf16_f32 v135, v4, v5
	v_add_u32_e32 v4, 0x400, v142
	ds_read2_b32 v[136:137], v4 offset0:4 offset1:69
	v_cmp_lt_i32_e32 vcc, s4, v150
	v_lshlrev_b32_e32 v2, 1, v140
	s_waitcnt lgkmcnt(0)
	v_cvt_pk_bf16_f32 v136, v136, v137
	ds_read2_b32 v[160:161], v4 offset0:134 offset1:199
	s_waitcnt lgkmcnt(0)
	v_cvt_pk_bf16_f32 v137, v160, v161
	s_and_saveexec_b64 s[14:15], vcc
	s_cbranch_execz .LBB0_698
	v_add_u32_e32 v160, s17, v141
	v_ashrrev_i32_e32 v161, 31, v160
	v_lshlrev_b64 v[160:161], 12, v[160:161]
	v_lshl_add_u64 v[160:161], s[2:3], 0, v[160:161]
	s_ashr_i32 s7, s6, 31
	v_lshl_add_u64 v[160:161], s[6:7], 1, v[160:161]
	v_lshl_add_u64 v[160:161], v[160:161], 0, v[2:3]
	global_store_dwordx4 v[160:161], v[134:137], off

;     ...
;     for (; it < it1; it += NGW) {
;         const bool more = it + NGW < it1;
;         if (more) { TR_DESCRIBE(it + NGW, tn); tr_load(tn, vn, lane); }
;         tr_finish(tc, vc, scr, lane);
;         if (more) { tc = tn;
; #pragma unroll
;             for (int i = 0; i < 16; ++i) vc[i] = vn[i]; }
.LBB0_712:
	s_or_b64 exec, exec, s[14:15]
	s_waitcnt lgkmcnt(0)
	s_andn2_b64 vcc, exec, s[12:13]
	s_cbranch_vccnz .LBB0_677
	s_waitcnt vmcnt(0)
	v_mov_b64_e32 v[66:67], v[130:131]
	v_mov_b64_e32 v[62:63], v[126:127]
	v_mov_b64_e32 v[58:59], v[118:119]
	v_mov_b64_e32 v[54:55], v[122:123]
	v_mov_b64_e32 v[50:51], v[110:111]
	v_mov_b64_e32 v[46:47], v[114:115]
	v_mov_b64_e32 v[42:43], v[102:103]
	v_mov_b64_e32 v[38:39], v[106:107]
	v_mov_b64_e32 v[34:35], v[94:95]
	v_mov_b64_e32 v[30:31], v[98:99]
	v_mov_b64_e32 v[26:27], v[86:87]
	v_mov_b64_e32 v[22:23], v[90:91]
	v_mov_b64_e32 v[18:19], v[70:71]
	v_mov_b64_e32 v[14:15], v[82:83]
	v_mov_b64_e32 v[10:11], v[74:75]
	v_mov_b64_e32 v[6:7], v[78:79]
	v_mov_b64_e32 v[68:69], v[132:133]
	v_mov_b64_e32 v[64:65], v[128:129]
	v_mov_b64_e32 v[60:61], v[120:121]
	v_mov_b64_e32 v[56:57], v[124:125]
	v_mov_b64_e32 v[52:53], v[112:113]
	v_mov_b64_e32 v[48:49], v[116:117]
	v_mov_b64_e32 v[44:45], v[104:105]
	v_mov_b64_e32 v[40:41], v[108:109]
	v_mov_b64_e32 v[36:37], v[96:97]
	v_mov_b64_e32 v[32:33], v[100:101]
	v_mov_b64_e32 v[28:29], v[88:89]
	v_mov_b64_e32 v[24:25], v[92:93]
	v_mov_b64_e32 v[20:21], v[72:73]
	v_mov_b64_e32 v[16:17], v[84:85]
	v_mov_b64_e32 v[12:13], v[76:77]
	v_mov_b64_e32 v[8:9], v[80:81]
	s_mov_b32 s6, s19
	s_mov_b32 s17, s9
	s_mov_b32 s4, s8
	s_branch .LBB0_677

;     ...
;     TrItem tc, tn; f32x4 vc[16], vn[16];
;     int it = it0 + gw;
;     if (it < it1) { TR_DESCRIBE(it, tc); tr_load(tc, vc, lane); }
;     for (; it < it1; it += NGW) {
;         const bool more = it + NGW < it1;
;         if (more) { TR_DESCRIBE(it + NGW, tn); tr_load(tn, vn, lane); }
.LBB0_1468:
	s_waitcnt vmcnt(0)
	s_add_i32 s27, s27, s39
	s_cmpk_lt_i32 s27, 0x2100
	s_cselect_b64 s[20:21], -1, 0
	s_cmpk_gt_i32 s27, 0x20ff
	s_cselect_b64 s[18:19], -1, 0
	s_and_b64 vcc, exec, s[18:19]
	s_cbranch_vccnz .LBB0_1491
	s_cmpk_gt_i32 s27, 0x15ff
	s_mov_b64 s[16:17], -1
	s_cbranch_scc0 .LBB0_1471
	s_and_b32 s9, s33, 0x7fc0
	s_and_b32 s14, s11, 0x7c0
	s_add_i32 s35, s9, 0xffffd400
	s_mov_b64 s[16:17], 0

; #define LAS __attribute__((address_space(3)))
; __device__ __forceinline__ unsigned pk2(float lo, float hi) { return cvtpk(lo, hi); }
; __device__ __forceinline__ void tr_finish(const TrItem& t, const f32x4 (&v)[16], LAS float* scr, int lane) {
;     const int c4 = 4 * (lane & 15), kq = lane >> 4;
; #pragma unroll
;     for (int i = 0; i < 16; ++i) { LAS float* d = scr + (4 * i + kq) * 65 + c4; d[0] = v[i].x; d[1] = v[i].y; d[2] = v[i].z; d[3] = v[i].w; }
;     asm volatile("s_waitcnt lgkmcnt(0)" ::: "memory");
;     const int c = lane & 7;
; #pragma unroll
;     for (int j = 0; j < 8; ++j) { const int n = (lane >> 3) + 8 * j; const LAS float* s = scr + (8 * c) * 65 + n;
;         v4u o; o.x = pk2(s[0 * 65], s[1 * 65]); o.y = pk2(s[2 * 65], s[3 * 65]); o.z = pk2(s[4 * 65], s[5 * 65]); o.w = pk2(s[6 * 65], s[7 * 65]);
;         if (t.n0 + n < t.N) *(v4u*)(t.WT + (size_t)(t.drow0 + n) * t.K + t.k0 + 8 * c) = o; }
;     asm volatile("s_waitcnt lgkmcnt(0)" ::: "memory");
.LBB0_1491:
	v_add_u32_e32 v2, 0x410, v165
	ds_write2_b32 v165, v6, v7 offset1:1
	ds_write2_b32 v165, v8, v9 offset0:2 offset1:3
	ds_write2_b32 v2, v10, v11 offset1:1
	v_add_u32_e32 v2, 0x418, v165
	ds_write2_b32 v2, v12, v13 offset1:1
	v_add_u32_e32 v2, 0x820, v165
	ds_write2_b32 v2, v14, v15 offset1:1
	v_add_u32_e32 v2, 0x828, v165
	ds_write2_b32 v2, v16, v17 offset1:1
	v_add_u32_e32 v2, 0xc30, v165
	ds_write2_b32 v2, v18, v19 offset1:1
	v_add_u32_e32 v2, 0xc38, v165
	ds_write2_b32 v2, v20, v21 offset1:1
	v_add_u32_e32 v2, 0x1040, v165
	ds_write2_b32 v2, v22, v23 offset1:1
	v_add_u32_e32 v2, 0x1048, v165
	ds_write2_b32 v2, v24, v25 offset1:1
	v_add_u32_e32 v2, 0x1450, v165
	ds_write2_b32 v2, v26, v27 offset1:1
	v_add_u32_e32 v2, 0x1458, v165
	ds_write2_b32 v2, v28, v29 offset1:1
	v_add_u32_e32 v2, 0x1860, v165
	ds_write2_b32 v2, v30, v31 offset1:1
	v_add_u32_e32 v2, 0x1868, v165
	ds_write2_b32 v2, v32, v33 offset1:1
	v_add_u32_e32 v2, 0x1c70, v165
	ds_write2_b32 v2, v34, v35 offset1:1
	v_add_u32_e32 v2, 0x1c78, v165
	ds_write2_b32 v2, v36, v37 offset1:1
	v_add_u32_e32 v2, 0x2080, v165
	ds_write2_b32 v2, v38, v39 offset1:1
	v_add_u32_e32 v2, 0x2088, v165
	ds_write2_b32 v2, v40, v41 offset1:1
	v_add_u32_e32 v2, 0x2490, v165
	ds_write2_b32 v2, v42, v43 offset1:1
	v_add_u32_e32 v2, 0x2498, v165
	ds_write2_b32 v2, v44, v45 offset1:1
	v_add_u32_e32 v2, 0x28a0, v165
	ds_write2_b32 v2, v46, v47 offset1:1
	v_add_u32_e32 v2, 0x28a8, v165
	ds_write2_b32 v2, v48, v49 offset1:1
	v_add_u32_e32 v2, 0x2cb0, v165
	ds_write2_b32 v2, v50, v51 offset1:1
	v_add_u32_e32 v2, 0x2cb8, v165
	ds_write2_b32 v2, v52, v53 offset1:1
	v_add_u32_e32 v2, 0x30c0, v165
	ds_write2_b32 v2, v54, v55 offset1:1
	v_add_u32_e32 v2, 0x30c8, v165
	ds_write2_b32 v2, v56, v57 offset1:1
	v_add_u32_e32 v2, 0x34d0, v165
	ds_write2_b32 v2, v58, v59 offset1:1
	v_add_u32_e32 v2, 0x34d8, v165
	ds_write2_b32 v2, v60, v61 offset1:1
	v_add_u32_e32 v2, 0x38e0, v165
	ds_write2_b32 v2, v62, v63 offset1:1
	v_add_u32_e32 v2, 0x38e8, v165
	ds_write2_b32 v2, v64, v65 offset1:1
	v_add_u32_e32 v2, 0x3cf0, v165
	ds_write2_b32 v2, v66, v67 offset1:1
	v_add_u32_e32 v2, 0x3cf8, v165
	ds_write2_b32 v2, v68, v69 offset1:1
	s_waitcnt lgkmcnt(0)
	ds_read2_b32 v[4:5], v157 offset1:65
	s_waitcnt lgkmcnt(0)
	v_cvt_pk_bf16_f32 v134, v4, v5
	ds_read2_b32 v[4:5], v157 offset0:130 offset1:195
	s_waitcnt lgkmcnt(0)
	v_cvt_pk_bf16_f32 v135, v4, v5
	v_add_u32_e32 v4, 0x400, v157
	v_add_u32_e32 v2, s10, v156
	ds_read2_b32 v[136:137], v4 offset0:4 offset1:69
	v_cmp_gt_i32_e32 vcc, s30, v2
	v_lshlrev_b32_e32 v2, 1, v140
	s_waitcnt lgkmcnt(0)
	v_cvt_pk_bf16_f32 v136, v136, v137
	ds_read2_b32 v[166:167], v4 offset0:134 offset1:199
	s_waitcnt lgkmcnt(0)
	v_cvt_pk_bf16_f32 v137, v166, v167
	s_and_saveexec_b64 s[22:23], vcc
	s_cbranch_execz .LBB0_1493
	v_add_u32_e32 v5, s28, v156
	v_mad_i64_i32 v[166:167], s[24:25], v5, s29, 0
	v_lshl_add_u64 v[166:167], v[166:167], 1, s[12:13]
	s_ashr_i32 s9, s8, 31
	v_lshl_add_u64 v[166:167], s[8:9], 1, v[166:167]
	v_lshl_add_u64 v[166:167], v[166:167], 0, v[2:3]
	global_store_dwordx4 v[166:167], v[134:137], off

;     ...
;     for (; it < it1; it += NGW) {
;         const bool more = it + NGW < it1;
;         if (more) { TR_DESCRIBE(it + NGW, tn); tr_load(tn, vn, lane); }
;         tr_finish(tc, vc, scr, lane);
;         if (more) { tc = tn;
; #pragma unroll
;             for (int i = 0; i < 16; ++i) vc[i] = vn[i]; }
.LBB0_1507:
	s_or_b64 exec, exec, s[22:23]
	s_waitcnt lgkmcnt(0)
	s_andn2_b64 vcc, exec, s[20:21]
	s_cbranch_vccnz .LBB0_1467
	s_waitcnt vmcnt(0)
	v_mov_b64_e32 v[66:67], v[130:131]
	v_mov_b64_e32 v[62:63], v[126:127]
	v_mov_b64_e32 v[58:59], v[118:119]
	v_mov_b64_e32 v[54:55], v[122:123]
	v_mov_b64_e32 v[50:51], v[110:111]
	v_mov_b64_e32 v[46:47], v[114:115]
	v_mov_b64_e32 v[42:43], v[102:103]
	v_mov_b64_e32 v[38:39], v[106:107]
	v_mov_b64_e32 v[34:35], v[94:95]
	v_mov_b64_e32 v[30:31], v[98:99]
	v_mov_b64_e32 v[26:27], v[86:87]
	v_mov_b64_e32 v[22:23], v[90:91]
	v_mov_b64_e32 v[18:19], v[78:79]
	v_mov_b64_e32 v[14:15], v[82:83]
	v_mov_b64_e32 v[10:11], v[70:71]
	v_mov_b64_e32 v[6:7], v[74:75]
	v_mov_b64_e32 v[68:69], v[132:133]
	v_mov_b64_e32 v[64:65], v[128:129]
	v_mov_b64_e32 v[60:61], v[120:121]
	v_mov_b64_e32 v[56:57], v[124:125]
	v_mov_b64_e32 v[52:53], v[112:113]
	v_mov_b64_e32 v[48:49], v[116:117]
	v_mov_b64_e32 v[44:45], v[104:105]
	v_mov_b64_e32 v[40:41], v[108:109]
	v_mov_b64_e32 v[36:37], v[96:97]
	v_mov_b64_e32 v[32:33], v[100:101]
	v_mov_b64_e32 v[28:29], v[88:89]
	v_mov_b64_e32 v[24:25], v[92:93]
	v_mov_b64_e32 v[20:21], v[80:81]
	v_mov_b64_e32 v[16:17], v[84:85]
	v_mov_b64_e32 v[12:13], v[72:73]
	v_mov_b64_e32 v[8:9], v[76:77]
	s_mov_b32 s8, s35
	s_mov_b32 s28, s38
	s_mov_b32 s30, s37
	s_mov_b32 s29, s36
	s_mov_b64 s[12:13], s[16:17]
	s_mov_b32 s10, s14
	s_branch .LBB0_1467

;     ...
;     TrItem tc, tn; f32x4 vc[16], vn[16];
;     int it = it0 + gw;
;     if (it < it1) { TR_DESCRIBE(it, tc); tr_load(tc, vc, lane); }
;     for (; it < it1; it += NGW) {
;         const bool more = it + NGW < it1;
;         if (more) { TR_DESCRIBE(it + NGW, tn); tr_load(tn, vn, lane); }
.LBB0_1629:
	s_waitcnt vmcnt(0)
	v_readlane_b32 s13, v252, 51
	s_add_i32 s31, s13, s31
	s_cmpk_lt_i32 s31, 0x2c20
	s_cselect_b64 s[24:25], -1, 0
	s_cmpk_gt_i32 s31, 0x2c1f
	s_cselect_b64 s[22:23], -1, 0
	s_and_b64 vcc, exec, s[22:23]
	s_cbranch_vccnz .LBB0_1654
	s_cmpk_gt_i32 s31, 0x15ff
	s_mov_b64 s[28:29], -1
	s_cbranch_scc0 .LBB0_1635
	s_cmpk_gt_u32 s31, 0x20ff
	s_mov_b64 s[20:21], -1
	s_cbranch_scc0 .LBB0_1633
	s_add_i32 s13, s31, 0xdf00
	s_and_b32 s18, s13, 0xffff
	s_mulk_i32 s18, 0x702f
	s_lshr_b32 s18, s18, 16
	s_sub_i32 s19, s13, s18
	s_bfe_u32 s19, s19, 0xf0001
	s_add_i32 s19, s19, s18
	s_bfe_u32 s18, s19, 0xa0006
	s_mulk_i32 s18, 0x59
	s_sub_i32 s13, s13, s18
	s_lshl_b32 s13, s13, 6
	s_and_b32 s18, s13, 0xffc0
	s_and_b32 s39, s19, 0xffc0
	s_mov_b64 s[20:21], 0

; #define LAS __attribute__((address_space(3)))
; __device__ __forceinline__ unsigned pk2(float lo, float hi) { return cvtpk(lo, hi); }
; __device__ __forceinline__ void tr_finish(const TrItem& t, const f32x4 (&v)[16], LAS float* scr, int lane) {
;     const int c4 = 4 * (lane & 15), kq = lane >> 4;
; #pragma unroll
;     for (int i = 0; i < 16; ++i) { LAS float* d = scr + (4 * i + kq) * 65 + c4; d[0] = v[i].x; d[1] = v[i].y; d[2] = v[i].z; d[3] = v[i].w; }
;     asm volatile("s_waitcnt lgkmcnt(0)" ::: "memory");
;     const int c = lane & 7;
; #pragma unroll
;     for (int j = 0; j < 8; ++j) { const int n = (lane >> 3) + 8 * j; const LAS float* s = scr + (8 * c) * 65 + n;
;         v4u o; o.x = pk2(s[0 * 65], s[1 * 65]); o.y = pk2(s[2 * 65], s[3 * 65]); o.z = pk2(s[4 * 65], s[5 * 65]); o.w = pk2(s[6 * 65], s[7 * 65]);
;         if (t.n0 + n < t.N) *(v4u*)(t.WT + (size_t)(t.drow0 + n) * t.K + t.k0 + 8 * c) = o; }
;     asm volatile("s_waitcnt lgkmcnt(0)" ::: "memory");
.LBB0_1654:
	v_add_u32_e32 v2, 0x410, v165
	ds_write2_b32 v165, v6, v7 offset1:1
	ds_write2_b32 v165, v8, v9 offset0:2 offset1:3
	ds_write2_b32 v2, v10, v11 offset1:1
	v_add_u32_e32 v2, 0x418, v165
	ds_write2_b32 v2, v12, v13 offset1:1
	v_add_u32_e32 v2, 0x820, v165
	ds_write2_b32 v2, v14, v15 offset1:1
	v_add_u32_e32 v2, 0x828, v165
	ds_write2_b32 v2, v16, v17 offset1:1
	v_add_u32_e32 v2, 0xc30, v165
	ds_write2_b32 v2, v18, v19 offset1:1
	v_add_u32_e32 v2, 0xc38, v165
	ds_write2_b32 v2, v20, v21 offset1:1
	v_add_u32_e32 v2, 0x1040, v165
	ds_write2_b32 v2, v22, v23 offset1:1
	v_add_u32_e32 v2, 0x1048, v165
	ds_write2_b32 v2, v24, v25 offset1:1
	v_add_u32_e32 v2, 0x1450, v165
	ds_write2_b32 v2, v26, v27 offset1:1
	v_add_u32_e32 v2, 0x1458, v165
	ds_write2_b32 v2, v28, v29 offset1:1
	v_add_u32_e32 v2, 0x1860, v165
	ds_write2_b32 v2, v30, v31 offset1:1
	v_add_u32_e32 v2, 0x1868, v165
	ds_write2_b32 v2, v32, v33 offset1:1
	v_add_u32_e32 v2, 0x1c70, v165
	ds_write2_b32 v2, v34, v35 offset1:1
	v_add_u32_e32 v2, 0x1c78, v165
	ds_write2_b32 v2, v36, v37 offset1:1
	v_add_u32_e32 v2, 0x2080, v165
	ds_write2_b32 v2, v38, v39 offset1:1
	v_add_u32_e32 v2, 0x2088, v165
	ds_write2_b32 v2, v40, v41 offset1:1
	v_add_u32_e32 v2, 0x2490, v165
	ds_write2_b32 v2, v42, v43 offset1:1
	v_add_u32_e32 v2, 0x2498, v165
	ds_write2_b32 v2, v44, v45 offset1:1
	v_add_u32_e32 v2, 0x28a0, v165
	ds_write2_b32 v2, v46, v47 offset1:1
	v_add_u32_e32 v2, 0x28a8, v165
	ds_write2_b32 v2, v48, v49 offset1:1
	v_add_u32_e32 v2, 0x2cb0, v165
	ds_write2_b32 v2, v50, v51 offset1:1
	v_add_u32_e32 v2, 0x2cb8, v165
	ds_write2_b32 v2, v52, v53 offset1:1
	v_add_u32_e32 v2, 0x30c0, v165
	ds_write2_b32 v2, v54, v55 offset1:1
	v_add_u32_e32 v2, 0x30c8, v165
	ds_write2_b32 v2, v56, v57 offset1:1
	v_add_u32_e32 v2, 0x34d0, v165
	ds_write2_b32 v2, v58, v59 offset1:1
	v_add_u32_e32 v2, 0x34d8, v165
	ds_write2_b32 v2, v60, v61 offset1:1
	v_add_u32_e32 v2, 0x38e0, v165
	ds_write2_b32 v2, v62, v63 offset1:1
	v_add_u32_e32 v2, 0x38e8, v165
	ds_write2_b32 v2, v64, v65 offset1:1
	v_add_u32_e32 v2, 0x3cf0, v165
	ds_write2_b32 v2, v66, v67 offset1:1
	v_add_u32_e32 v2, 0x3cf8, v165
	ds_write2_b32 v2, v68, v69 offset1:1
	s_waitcnt lgkmcnt(0)
	ds_read2_b32 v[4:5], v157 offset1:65
	s_waitcnt lgkmcnt(0)
	v_cvt_pk_bf16_f32 v134, v4, v5
	ds_read2_b32 v[4:5], v157 offset0:130 offset1:195
	s_waitcnt lgkmcnt(0)
	v_cvt_pk_bf16_f32 v135, v4, v5
	v_add_u32_e32 v4, 0x400, v157
	v_add_u32_e32 v2, s16, v156
	ds_read2_b32 v[136:137], v4 offset0:4 offset1:69
	v_cmp_gt_i32_e32 vcc, s35, v2
	v_lshlrev_b32_e32 v2, 1, v140
	s_waitcnt lgkmcnt(0)
	v_cvt_pk_bf16_f32 v136, v136, v137
	ds_read2_b32 v[166:167], v4 offset0:134 offset1:199
	s_waitcnt lgkmcnt(0)
	v_cvt_pk_bf16_f32 v137, v166, v167
	s_and_saveexec_b64 s[26:27], vcc
	s_cbranch_execz .LBB0_1656
	v_add_u32_e32 v5, s33, v156
	v_mad_i64_i32 v[166:167], s[28:29], v5, s34, 0
	v_lshl_add_u64 v[166:167], v[166:167], 1, s[14:15]
	s_ashr_i32 s13, s12, 31
	v_lshl_add_u64 v[166:167], s[12:13], 1, v[166:167]
	v_lshl_add_u64 v[166:167], v[166:167], 0, v[2:3]
	global_store_dwordx4 v[166:167], v[134:137], off

;     ...
;     for (; it < it1; it += NGW) {
;         const bool more = it + NGW < it1;
;         if (more) { TR_DESCRIBE(it + NGW, tn); tr_load(tn, vn, lane); }
;         tr_finish(tc, vc, scr, lane);
;         if (more) { tc = tn;
; #pragma unroll
;             for (int i = 0; i < 16; ++i) vc[i] = vn[i]; }
.LBB0_1670:
	s_or_b64 exec, exec, s[26:27]
	s_waitcnt lgkmcnt(0)
	s_andn2_b64 vcc, exec, s[24:25]
	s_cbranch_vccnz .LBB0_1628
	s_waitcnt vmcnt(0)
	v_mov_b64_e32 v[66:67], v[130:131]
	v_mov_b64_e32 v[62:63], v[126:127]
	v_mov_b64_e32 v[58:59], v[118:119]
	v_mov_b64_e32 v[54:55], v[122:123]
	v_mov_b64_e32 v[50:51], v[110:111]
	v_mov_b64_e32 v[46:47], v[114:115]
	v_mov_b64_e32 v[42:43], v[102:103]
	v_mov_b64_e32 v[38:39], v[106:107]
	v_mov_b64_e32 v[34:35], v[94:95]
	v_mov_b64_e32 v[30:31], v[98:99]
	v_mov_b64_e32 v[26:27], v[86:87]
	v_mov_b64_e32 v[22:23], v[90:91]
	v_mov_b64_e32 v[18:19], v[78:79]
	v_mov_b64_e32 v[14:15], v[82:83]
	v_mov_b64_e32 v[10:11], v[70:71]
	v_mov_b64_e32 v[6:7], v[74:75]
	v_mov_b64_e32 v[68:69], v[132:133]
	v_mov_b64_e32 v[64:65], v[128:129]
	v_mov_b64_e32 v[60:61], v[120:121]
	v_mov_b64_e32 v[56:57], v[124:125]
	v_mov_b64_e32 v[52:53], v[112:113]
	v_mov_b64_e32 v[48:49], v[116:117]
	v_mov_b64_e32 v[44:45], v[104:105]
	v_mov_b64_e32 v[40:41], v[108:109]
	v_mov_b64_e32 v[36:37], v[96:97]
	v_mov_b64_e32 v[32:33], v[100:101]
	v_mov_b64_e32 v[28:29], v[88:89]
	v_mov_b64_e32 v[24:25], v[92:93]
	v_mov_b64_e32 v[20:21], v[80:81]
	v_mov_b64_e32 v[16:17], v[84:85]
	v_mov_b64_e32 v[12:13], v[72:73]
	v_mov_b64_e32 v[8:9], v[76:77]
	s_mov_b32 s12, s39
	s_mov_b32 s33, s42
	s_mov_b32 s35, s41
	s_mov_b32 s34, s40
	s_mov_b64 s[14:15], s[20:21]
	s_mov_b32 s16, s18
	s_branch .LBB0_1628
